# speedup vs baseline: 1.0103x; 1.0014x over previous
; __device__ __forceinline__ unsigned cvt_pk_bf16(float lo, float hi) { unsigned r; asm volatile("v_cvt_pk_bf16_f32 %0, %1, %2" : "=v"(r) : "v"(lo), "v"(hi)); return r; }
;     __device__ __forceinline__ void operator()(const f32x4 (&acc)[2][2][4][2], const Unit& u, int wr, int wc, int fr, int fq) const {
;     ...
;         const int col0 = u.pn * HALF + wc * 32 + 8 * fq;
; #pragma unroll
;         for (int ai = 0; ai < 2; ++ai)
; #pragma unroll
;             for (int m = 0; m < 4; ++m) { bf16_t* rowp = O + (size_t)(row0 + ai * HALF + m * 16) * ldc + col0;
;                 f32x2 h[4];
; #pragma unroll
;                 for (int n = 0; n < 2; ++n)
; #pragma unroll
;                     for (int j = 0; j < 2; ++j) { const f32x2 g = {acc[ai][0][m][n][2 * j], acc[ai][0][m][n][2 * j + 1]}, up = {acc[ai][1][m][n][2 * j], acc[ai][1][m][n][2 * j + 1]};
;                         const f32x2 t = g * (-1.44269504089f); f32x2 e; e.x = __builtin_amdgcn_exp2f(t.x); e.y = __builtin_amdgcn_exp2f(t.y);
;                         const f32x2 d = e + 1.0f; f32x2 r; r.x = __builtin_amdgcn_rcpf(d.x); r.y = __builtin_amdgcn_rcpf(d.y);
;                         h[n * 2 + j] = (g * r) * up; }
;                 u32x4 w; w.x = cvt_pk_bf16(h[0].x, h[0].y); w.y = cvt_pk_bf16(h[1].x, h[1].y); w.z = cvt_pk_bf16(h[2].x, h[2].y); w.w = cvt_pk_bf16(h[3].x, h[3].y);
;                 *(u32x4*)rowp = w; }
.LBB0_362:
	v_lshrrev_b32_e32 v254, 2, v206
	v_and_b32_e32 v255, 15, v206
	v_sub_u32_e32 v252, v254, v255
	v_mul_lo_u32 v252, v252, s20
	v_lshlrev_b32_e32 v252, 1, v252
	v_and_b32_e32 v253, 3, v206
	v_lshrrev_b32_e32 v255, 4, v206
	v_sub_u32_e32 v253, v253, v255
	v_lshl_add_u32 v252, v253, 4, v252
	v_ashrrev_i32_e32 v253, 31, v252
	v_lshrrev_b32_e32 v255, 6, v180
	v_mul_u32_u24_e32 v255, 0x500, v255
	v_add_u32_e32 v255, 0x20000, v255
	v_and_b32_e32 v244, 15, v206
	v_mul_u32_u24_e32 v244, 0x50, v244
	v_lshrrev_b32_e32 v245, 4, v206
	v_lshl_add_u32 v244, v245, 4, v244
	v_add_u32_e32 v244, v244, v255
	v_mul_u32_u24_e32 v245, 0x50, v254
	v_and_b32_e32 v254, 3, v206
	v_lshl_add_u32 v245, v254, 4, v245
	v_add_u32_e32 v245, v245, v255
	v_lshl_add_u32 v148, s31, 8, v144
	s_cmp_lt_i32 s30, 0
	s_mov_b64 s[38:39], -1
	s_mov_b32 s60, 0x14000
	s_cbranch_scc0 .LBB0_369
	v_mad_i64_i32 v[140:141], s[18:19], s20, v148, 0
	v_lshl_add_u64 v[140:141], v[140:141], 1, s[8:9]
	s_and_b64 vcc, exec, s[26:27]
	v_or_b32_e32 v155, 16, v148
	v_or_b32_e32 v154, 32, v148
	v_or_b32_e32 v153, 48, v148
	v_add_u32_e32 v152, 0x80, v148
	v_add_u32_e32 v151, 0x90, v148
	v_add_u32_e32 v150, 0xa0, v148
	v_add_u32_e32 v149, 0xb0, v148
	s_cbranch_vccz .LBB0_365
	v_pk_mul_f32 v[156:157], v[126:127], s[92:93] op_sel_hi:[1,0]
	v_pk_mul_f32 v[158:159], v[128:129], s[92:93] op_sel_hi:[1,0]
	v_exp_f32_e32 v156, v156
	v_exp_f32_e32 v157, v157
	v_exp_f32_e32 v158, v158
	v_exp_f32_e32 v159, v159
	v_pk_mul_f32 v[160:161], v[122:123], s[92:93] op_sel_hi:[1,0]
	v_pk_mul_f32 v[162:163], v[124:125], s[92:93] op_sel_hi:[1,0]
	v_exp_f32_e32 v160, v160
	v_exp_f32_e32 v161, v161
	v_exp_f32_e32 v162, v162
	v_exp_f32_e32 v163, v163
	v_pk_add_f32 v[156:157], v[156:157], 1.0 op_sel_hi:[1,0]
	v_pk_add_f32 v[158:159], v[158:159], 1.0 op_sel_hi:[1,0]
	v_rcp_f32_e32 v156, v156
	v_rcp_f32_e32 v157, v157
	v_rcp_f32_e32 v158, v158
	v_rcp_f32_e32 v159, v159
	v_pk_add_f32 v[160:161], v[160:161], 1.0 op_sel_hi:[1,0]
	v_pk_add_f32 v[162:163], v[162:163], 1.0 op_sel_hi:[1,0]
	v_rcp_f32_e32 v160, v160
	v_rcp_f32_e32 v161, v161
	v_rcp_f32_e32 v162, v162
	v_rcp_f32_e32 v163, v163
	v_lshl_or_b32 v142, s67, 7, v146
	v_ashrrev_i32_e32 v143, 31, v142
	v_pk_mul_f32 v[156:157], v[126:127], v[156:157]
	v_pk_mul_f32 v[158:159], v[128:129], v[158:159]
	v_pk_mul_f32 v[156:157], v[114:115], v[156:157]
	v_pk_mul_f32 v[158:159], v[116:117], v[158:159]
	v_pk_mul_f32 v[160:161], v[122:123], v[160:161]
	v_pk_mul_f32 v[162:163], v[124:125], v[162:163]
	v_lshlrev_b64 v[142:143], 1, v[142:143]
	v_pk_mul_f32 v[160:161], v[106:107], v[160:161]
	v_pk_mul_f32 v[162:163], v[108:109], v[162:163]
	v_lshl_add_u64 v[164:165], v[140:141], 0, v[142:143]
	v_cvt_pk_bf16_f32 v156, v156, v157
	v_cvt_pk_bf16_f32 v157, v158, v159
	v_cvt_pk_bf16_f32 v158, v160, v161
	v_cvt_pk_bf16_f32 v159, v162, v163
	ds_write_b128 v244, v[156:159]
	v_lshl_add_u64 v[246:247], v[164:165], 0, v[252:253]
	ds_read_b128 v[248:251], v245
	v_pk_mul_f32 v[160:161], v[120:121], s[92:93] op_sel_hi:[1,0]
	v_pk_mul_f32 v[162:163], v[110:111], s[92:93] op_sel_hi:[1,0]
	v_pk_mul_f32 v[158:159], v[118:119], s[92:93] op_sel_hi:[1,0]
	v_pk_mul_f32 v[164:165], v[112:113], s[92:93] op_sel_hi:[1,0]
	v_exp_f32_e32 v158, v158
	v_exp_f32_e32 v159, v159
	v_exp_f32_e32 v160, v160
	v_exp_f32_e32 v161, v161
	v_exp_f32_e32 v162, v162
	v_exp_f32_e32 v163, v163
	v_exp_f32_e32 v164, v164
	v_exp_f32_e32 v165, v165
	v_pk_add_f32 v[158:159], v[158:159], 1.0 op_sel_hi:[1,0]
	v_pk_add_f32 v[160:161], v[160:161], 1.0 op_sel_hi:[1,0]
	v_rcp_f32_e32 v158, v158
	v_rcp_f32_e32 v159, v159
	v_pk_add_f32 v[162:163], v[162:163], 1.0 op_sel_hi:[1,0]
	v_pk_add_f32 v[164:165], v[164:165], 1.0 op_sel_hi:[1,0]
	v_rcp_f32_e32 v160, v160
	v_rcp_f32_e32 v161, v161
	v_rcp_f32_e32 v162, v162
	v_rcp_f32_e32 v163, v163
	v_rcp_f32_e32 v164, v164
	v_rcp_f32_e32 v165, v165
	v_mad_i64_i32 v[156:157], s[18:19], s20, v155, 0
	v_pk_mul_f32 v[158:159], v[118:119], v[158:159]
	v_lshl_add_u64 v[156:157], v[156:157], 1, s[8:9]
	v_pk_mul_f32 v[158:159], v[98:99], v[158:159]
	v_pk_mul_f32 v[160:161], v[120:121], v[160:161]
	v_pk_mul_f32 v[162:163], v[110:111], v[162:163]
	v_pk_mul_f32 v[164:165], v[112:113], v[164:165]
	v_pk_mul_f32 v[160:161], v[100:101], v[160:161]
	v_pk_mul_f32 v[162:163], v[90:91], v[162:163]
	v_pk_mul_f32 v[164:165], v[92:93], v[164:165]
	v_lshl_add_u64 v[166:167], v[156:157], 0, v[142:143]
	v_cvt_pk_bf16_f32 v156, v158, v159
	v_cvt_pk_bf16_f32 v157, v160, v161
	v_cvt_pk_bf16_f32 v158, v162, v163
	v_cvt_pk_bf16_f32 v159, v164, v165
	s_waitcnt lgkmcnt(0)
	global_store_dwordx4 v[246:247], v[248:251], off
	ds_write_b128 v244, v[156:159]
	v_lshl_add_u64 v[246:247], v[166:167], 0, v[252:253]
	ds_read_b128 v[248:251], v245
	v_pk_mul_f32 v[160:161], v[104:105], s[92:93] op_sel_hi:[1,0]
	v_pk_mul_f32 v[162:163], v[94:95], s[92:93] op_sel_hi:[1,0]
	v_pk_mul_f32 v[158:159], v[102:103], s[92:93] op_sel_hi:[1,0]
	v_pk_mul_f32 v[164:165], v[96:97], s[92:93] op_sel_hi:[1,0]
	v_exp_f32_e32 v158, v158
	v_exp_f32_e32 v159, v159
	v_exp_f32_e32 v160, v160
	v_exp_f32_e32 v161, v161
	v_exp_f32_e32 v162, v162
	v_exp_f32_e32 v163, v163
	v_exp_f32_e32 v164, v164
	v_exp_f32_e32 v165, v165
	v_pk_add_f32 v[158:159], v[158:159], 1.0 op_sel_hi:[1,0]
	v_pk_add_f32 v[160:161], v[160:161], 1.0 op_sel_hi:[1,0]
	v_rcp_f32_e32 v158, v158
	v_rcp_f32_e32 v159, v159
	v_pk_add_f32 v[162:163], v[162:163], 1.0 op_sel_hi:[1,0]
	v_pk_add_f32 v[164:165], v[164:165], 1.0 op_sel_hi:[1,0]
	v_rcp_f32_e32 v160, v160
	v_rcp_f32_e32 v161, v161
	v_rcp_f32_e32 v162, v162
	v_rcp_f32_e32 v163, v163
	v_rcp_f32_e32 v164, v164
	v_rcp_f32_e32 v165, v165
	v_mad_i64_i32 v[156:157], s[18:19], s20, v154, 0
	v_pk_mul_f32 v[158:159], v[102:103], v[158:159]
	v_lshl_add_u64 v[156:157], v[156:157], 1, s[8:9]
	v_pk_mul_f32 v[158:159], v[82:83], v[158:159]
	v_pk_mul_f32 v[160:161], v[104:105], v[160:161]
	v_pk_mul_f32 v[162:163], v[94:95], v[162:163]
	v_pk_mul_f32 v[164:165], v[96:97], v[164:165]
	v_pk_mul_f32 v[160:161], v[84:85], v[160:161]
	v_pk_mul_f32 v[162:163], v[74:75], v[162:163]
	v_pk_mul_f32 v[164:165], v[76:77], v[164:165]
	v_lshl_add_u64 v[166:167], v[156:157], 0, v[142:143]
	v_cvt_pk_bf16_f32 v156, v158, v159
	v_cvt_pk_bf16_f32 v157, v160, v161
	v_cvt_pk_bf16_f32 v158, v162, v163
	v_cvt_pk_bf16_f32 v159, v164, v165
	s_waitcnt lgkmcnt(0)
; __device__ __forceinline__ unsigned cvt_pk_bf16(float lo, float hi) { unsigned r; asm volatile("v_cvt_pk_bf16_f32 %0, %1, %2" : "=v"(r) : "v"(lo), "v"(hi)); return r; }
;     __device__ __forceinline__ void operator()(const f32x4 (&acc)[2][2][4][2], const Unit& u, int wr, int wc, int fr, int fq) const {
;     ...
;         const int col0 = u.pn * HALF + wc * 32 + 8 * fq;
; #pragma unroll
;         for (int ai = 0; ai < 2; ++ai)
; #pragma unroll
;             for (int m = 0; m < 4; ++m) { bf16_t* rowp = O + (size_t)(row0 + ai * HALF + m * 16) * ldc + col0;
;                 f32x2 h[4];
; #pragma unroll
;                 for (int n = 0; n < 2; ++n)
; #pragma unroll
;                     for (int j = 0; j < 2; ++j) { const f32x2 g = {acc[ai][0][m][n][2 * j], acc[ai][0][m][n][2 * j + 1]}, up = {acc[ai][1][m][n][2 * j], acc[ai][1][m][n][2 * j + 1]};
;                         const f32x2 t = g * (-1.44269504089f); f32x2 e; e.x = __builtin_amdgcn_exp2f(t.x); e.y = __builtin_amdgcn_exp2f(t.y);
;                         const f32x2 d = e + 1.0f; f32x2 r; r.x = __builtin_amdgcn_rcpf(d.x); r.y = __builtin_amdgcn_rcpf(d.y);
;                         h[n * 2 + j] = (g * r) * up; }
;                 u32x4 w; w.x = cvt_pk_bf16(h[0].x, h[0].y); w.y = cvt_pk_bf16(h[1].x, h[1].y); w.z = cvt_pk_bf16(h[2].x, h[2].y); w.w = cvt_pk_bf16(h[3].x, h[3].y);
;                 *(u32x4*)rowp = w; }
	global_store_dwordx4 v[246:247], v[248:251], off
	ds_write_b128 v244, v[156:159]
	v_lshl_add_u64 v[246:247], v[166:167], 0, v[252:253]
	ds_read_b128 v[248:251], v245
	v_pk_mul_f32 v[160:161], v[88:89], s[92:93] op_sel_hi:[1,0]
	v_pk_mul_f32 v[162:163], v[78:79], s[92:93] op_sel_hi:[1,0]
	v_pk_mul_f32 v[158:159], v[86:87], s[92:93] op_sel_hi:[1,0]
	v_pk_mul_f32 v[164:165], v[80:81], s[92:93] op_sel_hi:[1,0]
	v_exp_f32_e32 v158, v158
	v_exp_f32_e32 v159, v159
	v_exp_f32_e32 v160, v160
	v_exp_f32_e32 v161, v161
	v_exp_f32_e32 v162, v162
	v_exp_f32_e32 v163, v163
	v_exp_f32_e32 v164, v164
	v_exp_f32_e32 v165, v165
	v_pk_add_f32 v[158:159], v[158:159], 1.0 op_sel_hi:[1,0]
	v_pk_add_f32 v[160:161], v[160:161], 1.0 op_sel_hi:[1,0]
	v_rcp_f32_e32 v158, v158
	v_rcp_f32_e32 v159, v159
	v_pk_add_f32 v[162:163], v[162:163], 1.0 op_sel_hi:[1,0]
	v_pk_add_f32 v[164:165], v[164:165], 1.0 op_sel_hi:[1,0]
	v_rcp_f32_e32 v160, v160
	v_rcp_f32_e32 v161, v161
	v_rcp_f32_e32 v162, v162
	v_rcp_f32_e32 v163, v163
	v_rcp_f32_e32 v164, v164
	v_rcp_f32_e32 v165, v165
	v_mad_i64_i32 v[156:157], s[18:19], s20, v153, 0
	v_pk_mul_f32 v[158:159], v[86:87], v[158:159]
	v_lshl_add_u64 v[156:157], v[156:157], 1, s[8:9]
	v_pk_mul_f32 v[158:159], v[70:71], v[158:159]
	v_pk_mul_f32 v[160:161], v[88:89], v[160:161]
	v_pk_mul_f32 v[162:163], v[78:79], v[162:163]
	v_pk_mul_f32 v[164:165], v[80:81], v[164:165]
	v_pk_mul_f32 v[160:161], v[72:73], v[160:161]
	v_pk_mul_f32 v[162:163], v[66:67], v[162:163]
	v_pk_mul_f32 v[164:165], v[68:69], v[164:165]
	v_lshl_add_u64 v[166:167], v[156:157], 0, v[142:143]
	v_cvt_pk_bf16_f32 v156, v158, v159
	v_cvt_pk_bf16_f32 v157, v160, v161
	v_cvt_pk_bf16_f32 v158, v162, v163
	v_cvt_pk_bf16_f32 v159, v164, v165
	s_waitcnt lgkmcnt(0)
	global_store_dwordx4 v[246:247], v[248:251], off
	ds_write_b128 v244, v[156:159]
	v_lshl_add_u64 v[246:247], v[166:167], 0, v[252:253]
	ds_read_b128 v[248:251], v245
	v_pk_mul_f32 v[160:161], v[64:65], s[92:93] op_sel_hi:[1,0]
	v_pk_mul_f32 v[162:163], v[58:59], s[92:93] op_sel_hi:[1,0]
	v_pk_mul_f32 v[158:159], v[62:63], s[92:93] op_sel_hi:[1,0]
	v_pk_mul_f32 v[164:165], v[60:61], s[92:93] op_sel_hi:[1,0]
	v_exp_f32_e32 v158, v158
	v_exp_f32_e32 v159, v159
	v_exp_f32_e32 v160, v160
	v_exp_f32_e32 v161, v161
	v_exp_f32_e32 v162, v162
	v_exp_f32_e32 v163, v163
	v_exp_f32_e32 v164, v164
	v_exp_f32_e32 v165, v165
	v_pk_add_f32 v[158:159], v[158:159], 1.0 op_sel_hi:[1,0]
	v_pk_add_f32 v[160:161], v[160:161], 1.0 op_sel_hi:[1,0]
	v_rcp_f32_e32 v158, v158
	v_rcp_f32_e32 v159, v159
	v_pk_add_f32 v[162:163], v[162:163], 1.0 op_sel_hi:[1,0]
	v_pk_add_f32 v[164:165], v[164:165], 1.0 op_sel_hi:[1,0]
	v_rcp_f32_e32 v160, v160
	v_rcp_f32_e32 v161, v161
	v_rcp_f32_e32 v162, v162
	v_rcp_f32_e32 v163, v163
	v_rcp_f32_e32 v164, v164
	v_rcp_f32_e32 v165, v165
	v_mad_i64_i32 v[156:157], s[18:19], s20, v152, 0
	v_pk_mul_f32 v[158:159], v[62:63], v[158:159]
	v_lshl_add_u64 v[156:157], v[156:157], 1, s[8:9]
	v_pk_mul_f32 v[158:159], v[50:51], v[158:159]
	v_pk_mul_f32 v[160:161], v[64:65], v[160:161]
	v_pk_mul_f32 v[162:163], v[58:59], v[162:163]
	v_pk_mul_f32 v[164:165], v[60:61], v[164:165]
	v_pk_mul_f32 v[160:161], v[52:53], v[160:161]
	v_pk_mul_f32 v[162:163], v[42:43], v[162:163]
	v_pk_mul_f32 v[164:165], v[44:45], v[164:165]
	v_lshl_add_u64 v[166:167], v[156:157], 0, v[142:143]
	v_cvt_pk_bf16_f32 v156, v158, v159
	v_cvt_pk_bf16_f32 v157, v160, v161
	v_cvt_pk_bf16_f32 v158, v162, v163
	v_cvt_pk_bf16_f32 v159, v164, v165
	s_waitcnt lgkmcnt(0)
	global_store_dwordx4 v[246:247], v[248:251], off
	ds_write_b128 v244, v[156:159]
	v_lshl_add_u64 v[246:247], v[166:167], 0, v[252:253]
	ds_read_b128 v[248:251], v245
	v_pk_mul_f32 v[160:161], v[56:57], s[92:93] op_sel_hi:[1,0]
	v_pk_mul_f32 v[162:163], v[46:47], s[92:93] op_sel_hi:[1,0]
	v_pk_mul_f32 v[158:159], v[54:55], s[92:93] op_sel_hi:[1,0]
	v_pk_mul_f32 v[164:165], v[48:49], s[92:93] op_sel_hi:[1,0]
	v_exp_f32_e32 v158, v158
	v_exp_f32_e32 v159, v159
	v_exp_f32_e32 v160, v160
	v_exp_f32_e32 v161, v161
	v_exp_f32_e32 v162, v162
	v_exp_f32_e32 v163, v163
	v_exp_f32_e32 v164, v164
	v_exp_f32_e32 v165, v165
	v_pk_add_f32 v[158:159], v[158:159], 1.0 op_sel_hi:[1,0]
	v_pk_add_f32 v[160:161], v[160:161], 1.0 op_sel_hi:[1,0]
	v_rcp_f32_e32 v158, v158
	v_rcp_f32_e32 v159, v159
	v_pk_add_f32 v[162:163], v[162:163], 1.0 op_sel_hi:[1,0]
	v_pk_add_f32 v[164:165], v[164:165], 1.0 op_sel_hi:[1,0]
	v_rcp_f32_e32 v160, v160
	v_rcp_f32_e32 v161, v161
	v_rcp_f32_e32 v162, v162
	v_rcp_f32_e32 v163, v163
	v_rcp_f32_e32 v164, v164
	v_rcp_f32_e32 v165, v165
	v_mad_i64_i32 v[156:157], s[18:19], s20, v151, 0
	v_pk_mul_f32 v[158:159], v[54:55], v[158:159]
	v_lshl_add_u64 v[156:157], v[156:157], 1, s[8:9]
	v_pk_mul_f32 v[158:159], v[34:35], v[158:159]
	v_pk_mul_f32 v[160:161], v[56:57], v[160:161]
	v_pk_mul_f32 v[162:163], v[46:47], v[162:163]
	v_pk_mul_f32 v[164:165], v[48:49], v[164:165]
	v_pk_mul_f32 v[160:161], v[36:37], v[160:161]
	v_pk_mul_f32 v[162:163], v[26:27], v[162:163]
	v_pk_mul_f32 v[164:165], v[28:29], v[164:165]
	v_lshl_add_u64 v[166:167], v[156:157], 0, v[142:143]
	v_cvt_pk_bf16_f32 v156, v158, v159
	v_cvt_pk_bf16_f32 v157, v160, v161
	v_cvt_pk_bf16_f32 v158, v162, v163
	v_cvt_pk_bf16_f32 v159, v164, v165
	s_waitcnt lgkmcnt(0)
; __device__ __forceinline__ unsigned cvt_pk_bf16(float lo, float hi) { unsigned r; asm volatile("v_cvt_pk_bf16_f32 %0, %1, %2" : "=v"(r) : "v"(lo), "v"(hi)); return r; }
;     __device__ __forceinline__ void operator()(const f32x4 (&acc)[2][2][4][2], const Unit& u, int wr, int wc, int fr, int fq) const {
;     ...
;         const int col0 = u.pn * HALF + wc * 32 + 8 * fq;
; #pragma unroll
;         for (int ai = 0; ai < 2; ++ai)
; #pragma unroll
;             for (int m = 0; m < 4; ++m) { bf16_t* rowp = O + (size_t)(row0 + ai * HALF + m * 16) * ldc + col0;
;                 f32x2 h[4];
; #pragma unroll
;                 for (int n = 0; n < 2; ++n)
; #pragma unroll
;                     for (int j = 0; j < 2; ++j) { const f32x2 g = {acc[ai][0][m][n][2 * j], acc[ai][0][m][n][2 * j + 1]}, up = {acc[ai][1][m][n][2 * j], acc[ai][1][m][n][2 * j + 1]};
;                         const f32x2 t = g * (-1.44269504089f); f32x2 e; e.x = __builtin_amdgcn_exp2f(t.x); e.y = __builtin_amdgcn_exp2f(t.y);
;                         const f32x2 d = e + 1.0f; f32x2 r; r.x = __builtin_amdgcn_rcpf(d.x); r.y = __builtin_amdgcn_rcpf(d.y);
;                         h[n * 2 + j] = (g * r) * up; }
;                 u32x4 w; w.x = cvt_pk_bf16(h[0].x, h[0].y); w.y = cvt_pk_bf16(h[1].x, h[1].y); w.z = cvt_pk_bf16(h[2].x, h[2].y); w.w = cvt_pk_bf16(h[3].x, h[3].y);
;                 *(u32x4*)rowp = w; }
	global_store_dwordx4 v[246:247], v[248:251], off
	ds_write_b128 v244, v[156:159]
	v_lshl_add_u64 v[246:247], v[166:167], 0, v[252:253]
	ds_read_b128 v[248:251], v245
	v_pk_mul_f32 v[160:161], v[40:41], s[92:93] op_sel_hi:[1,0]
	v_pk_mul_f32 v[162:163], v[30:31], s[92:93] op_sel_hi:[1,0]
	v_pk_mul_f32 v[158:159], v[38:39], s[92:93] op_sel_hi:[1,0]
	v_pk_mul_f32 v[164:165], v[32:33], s[92:93] op_sel_hi:[1,0]
	v_exp_f32_e32 v158, v158
	v_exp_f32_e32 v159, v159
	v_exp_f32_e32 v160, v160
	v_exp_f32_e32 v161, v161
	v_exp_f32_e32 v162, v162
	v_exp_f32_e32 v163, v163
	v_exp_f32_e32 v164, v164
	v_exp_f32_e32 v165, v165
	v_pk_add_f32 v[158:159], v[158:159], 1.0 op_sel_hi:[1,0]
	v_pk_add_f32 v[160:161], v[160:161], 1.0 op_sel_hi:[1,0]
	v_rcp_f32_e32 v158, v158
	v_rcp_f32_e32 v159, v159
	v_pk_add_f32 v[162:163], v[162:163], 1.0 op_sel_hi:[1,0]
	v_pk_add_f32 v[164:165], v[164:165], 1.0 op_sel_hi:[1,0]
	v_rcp_f32_e32 v160, v160
	v_rcp_f32_e32 v161, v161
	v_rcp_f32_e32 v162, v162
	v_rcp_f32_e32 v163, v163
	v_rcp_f32_e32 v164, v164
	v_rcp_f32_e32 v165, v165
	v_mad_i64_i32 v[156:157], s[18:19], s20, v150, 0
	v_pk_mul_f32 v[158:159], v[38:39], v[158:159]
	v_lshl_add_u64 v[156:157], v[156:157], 1, s[8:9]
	v_pk_mul_f32 v[158:159], v[18:19], v[158:159]
	v_pk_mul_f32 v[160:161], v[40:41], v[160:161]
	v_pk_mul_f32 v[162:163], v[30:31], v[162:163]
	v_pk_mul_f32 v[164:165], v[32:33], v[164:165]
	v_pk_mul_f32 v[160:161], v[20:21], v[160:161]
	v_pk_mul_f32 v[162:163], v[10:11], v[162:163]
	v_pk_mul_f32 v[164:165], v[12:13], v[164:165]
	v_lshl_add_u64 v[166:167], v[156:157], 0, v[142:143]
	v_cvt_pk_bf16_f32 v156, v158, v159
	v_cvt_pk_bf16_f32 v157, v160, v161
	v_cvt_pk_bf16_f32 v158, v162, v163
	v_cvt_pk_bf16_f32 v159, v164, v165
	s_waitcnt lgkmcnt(0)
	global_store_dwordx4 v[246:247], v[248:251], off
	ds_write_b128 v244, v[156:159]
	v_lshl_add_u64 v[246:247], v[166:167], 0, v[252:253]
	ds_read_b128 v[248:251], v245
	v_pk_mul_f32 v[160:161], v[24:25], s[92:93] op_sel_hi:[1,0]
	v_pk_mul_f32 v[162:163], v[14:15], s[92:93] op_sel_hi:[1,0]
	v_pk_mul_f32 v[158:159], v[22:23], s[92:93] op_sel_hi:[1,0]
	v_pk_mul_f32 v[164:165], v[16:17], s[92:93] op_sel_hi:[1,0]
	v_exp_f32_e32 v158, v158
	v_exp_f32_e32 v159, v159
	v_exp_f32_e32 v160, v160
	v_exp_f32_e32 v161, v161
	v_exp_f32_e32 v162, v162
	v_exp_f32_e32 v163, v163
	v_exp_f32_e32 v164, v164
	v_exp_f32_e32 v165, v165
	v_pk_add_f32 v[158:159], v[158:159], 1.0 op_sel_hi:[1,0]
	v_pk_add_f32 v[160:161], v[160:161], 1.0 op_sel_hi:[1,0]
	v_rcp_f32_e32 v158, v158
	v_rcp_f32_e32 v159, v159
	v_pk_add_f32 v[162:163], v[162:163], 1.0 op_sel_hi:[1,0]
	v_pk_add_f32 v[164:165], v[164:165], 1.0 op_sel_hi:[1,0]
	v_rcp_f32_e32 v160, v160
	v_rcp_f32_e32 v161, v161
	v_rcp_f32_e32 v162, v162
	v_rcp_f32_e32 v163, v163
	v_rcp_f32_e32 v164, v164
	v_rcp_f32_e32 v165, v165
	v_mad_i64_i32 v[156:157], s[18:19], s20, v149, 0
	v_lshl_add_u64 v[156:157], v[156:157], 1, s[8:9]
	v_pk_mul_f32 v[158:159], v[22:23], v[158:159]
	v_pk_mul_f32 v[160:161], v[24:25], v[160:161]
	v_pk_mul_f32 v[158:159], v[6:7], v[158:159]
	v_pk_mul_f32 v[162:163], v[14:15], v[162:163]
	v_pk_mul_f32 v[164:165], v[16:17], v[164:165]
	v_lshl_add_u64 v[142:143], v[156:157], 0, v[142:143]
	v_pk_mul_f32 v[160:161], v[8:9], v[160:161]
	v_pk_mul_f32 v[162:163], v[2:3], v[162:163]
	v_pk_mul_f32 v[164:165], v[4:5], v[164:165]
	v_cvt_pk_bf16_f32 v156, v158, v159
	v_cvt_pk_bf16_f32 v157, v160, v161
	v_cvt_pk_bf16_f32 v158, v162, v163
	s_mov_b64 s[38:39], 0
	v_cvt_pk_bf16_f32 v159, v164, v165
	s_waitcnt lgkmcnt(0)
	global_store_dwordx4 v[246:247], v[248:251], off
	ds_write_b128 v244, v[156:159]
	v_lshl_add_u64 v[246:247], v[142:143], 0, v[252:253]
	ds_read_b128 v[248:251], v245
	s_waitcnt lgkmcnt(0)
	global_store_dwordx4 v[246:247], v[248:251], off
; __device__ __forceinline__ unsigned cvt_pk_bf16(float lo, float hi) { unsigned r; asm volatile("v_cvt_pk_bf16_f32 %0, %1, %2" : "=v"(r) : "v"(lo), "v"(hi)); return r; }
;     __device__ __forceinline__ void operator()(const f32x4 (&acc)[2][2][4][2], const Unit& u, int wr, int wc, int fr, int fq) const {
;     ...
;         if (!swiglu) {
;             const int col0 = u.pn * BM + wc * 32 + 8 * fq;
; #pragma unroll
;             for (int ai = 0; ai < 2; ++ai)
; #pragma unroll
;                 for (int m = 0; m < 4; ++m) { bf16_t* rowp = O + (size_t)(row0 + ai * HALF + m * 16) * ldc + col0;
; #pragma unroll
;                     for (int bj = 0; bj < 2; ++bj) { const f32x4 v0 = acc[ai][bj][m][0], v1 = acc[ai][bj][m][1];
;                         u32x4 w; w.x = cvt_pk_bf16(v0[0], v0[1]); w.y = cvt_pk_bf16(v0[2], v0[3]); w.z = cvt_pk_bf16(v1[0], v1[1]); w.w = cvt_pk_bf16(v1[2], v1[3]);
;                         *(u32x4*)(rowp + bj * HALF) = w; } }
.LBB0_365:
	s_andn2_b64 vcc, exec, s[38:39]
	s_cbranch_vccnz .LBB0_367
	v_lshl_or_b32 v142, s67, 8, v146
	v_ashrrev_i32_e32 v143, 31, v142
	v_lshlrev_b64 v[142:143], 1, v[142:143]
	v_lshl_add_u64 v[140:141], v[140:141], 0, v[142:143]
	v_cvt_pk_bf16_f32 v156, v126, v127
	v_cvt_pk_bf16_f32 v157, v128, v129
	v_cvt_pk_bf16_f32 v158, v122, v123
	v_cvt_pk_bf16_f32 v159, v124, v125
	ds_write_b128 v244, v[156:159]
	v_lshl_add_u64 v[246:247], v[140:141], 0, v[252:253]
	ds_read_b128 v[248:251], v245
	s_nop 1
	v_cvt_pk_bf16_f32 v156, v114, v115
	v_cvt_pk_bf16_f32 v157, v116, v117
	v_cvt_pk_bf16_f32 v158, v106, v107
	v_cvt_pk_bf16_f32 v159, v108, v109
	s_waitcnt lgkmcnt(0)
	global_store_dwordx4 v[246:247], v[248:251], off
	ds_write_b128 v244, v[156:159]
	v_lshl_add_u64 v[246:247], v[140:141], 0, v[252:253]
	ds_read_b128 v[248:251], v245
	v_mad_i64_i32 v[140:141], s[18:19], s20, v155, 0
	v_lshl_add_u64 v[140:141], v[140:141], 1, s[8:9]
	v_lshl_add_u64 v[140:141], v[140:141], 0, v[142:143]
	v_cvt_pk_bf16_f32 v156, v118, v119
	v_cvt_pk_bf16_f32 v157, v120, v121
	v_cvt_pk_bf16_f32 v158, v110, v111
	v_cvt_pk_bf16_f32 v159, v112, v113
	s_waitcnt lgkmcnt(0)
	global_store_dwordx4 v[246:247], v[248:251], off offset:256
	ds_write_b128 v244, v[156:159]
	v_lshl_add_u64 v[246:247], v[140:141], 0, v[252:253]
	ds_read_b128 v[248:251], v245
	s_nop 1
	v_cvt_pk_bf16_f32 v156, v98, v99
	v_cvt_pk_bf16_f32 v157, v100, v101
	v_cvt_pk_bf16_f32 v158, v90, v91
	v_cvt_pk_bf16_f32 v159, v92, v93
	s_waitcnt lgkmcnt(0)
	global_store_dwordx4 v[246:247], v[248:251], off
	ds_write_b128 v244, v[156:159]
	v_lshl_add_u64 v[246:247], v[140:141], 0, v[252:253]
	ds_read_b128 v[248:251], v245
	v_mad_i64_i32 v[140:141], s[18:19], s20, v154, 0
	v_lshl_add_u64 v[140:141], v[140:141], 1, s[8:9]
	v_lshl_add_u64 v[140:141], v[140:141], 0, v[142:143]
	v_cvt_pk_bf16_f32 v154, v102, v103
	v_cvt_pk_bf16_f32 v155, v104, v105
	v_cvt_pk_bf16_f32 v156, v94, v95
	v_cvt_pk_bf16_f32 v157, v96, v97
	s_waitcnt lgkmcnt(0)
	global_store_dwordx4 v[246:247], v[248:251], off offset:256
	ds_write_b128 v244, v[154:157]
	v_lshl_add_u64 v[246:247], v[140:141], 0, v[252:253]
	ds_read_b128 v[248:251], v245
	s_nop 1
	v_cvt_pk_bf16_f32 v154, v82, v83
	v_cvt_pk_bf16_f32 v155, v84, v85
	v_cvt_pk_bf16_f32 v156, v74, v75
	v_cvt_pk_bf16_f32 v157, v76, v77
	s_waitcnt lgkmcnt(0)
	global_store_dwordx4 v[246:247], v[248:251], off
	ds_write_b128 v244, v[154:157]
	v_lshl_add_u64 v[246:247], v[140:141], 0, v[252:253]
	ds_read_b128 v[248:251], v245
	v_mad_i64_i32 v[140:141], s[18:19], s20, v153, 0
	v_lshl_add_u64 v[140:141], v[140:141], 1, s[8:9]
	v_lshl_add_u64 v[140:141], v[140:141], 0, v[142:143]
	v_cvt_pk_bf16_f32 v154, v86, v87
	v_cvt_pk_bf16_f32 v155, v88, v89
	v_cvt_pk_bf16_f32 v156, v78, v79
	v_cvt_pk_bf16_f32 v157, v80, v81
	s_waitcnt lgkmcnt(0)
	global_store_dwordx4 v[246:247], v[248:251], off offset:256
	ds_write_b128 v244, v[154:157]
	v_lshl_add_u64 v[246:247], v[140:141], 0, v[252:253]
	ds_read_b128 v[248:251], v245
	s_nop 1
	v_cvt_pk_bf16_f32 v154, v70, v71
	v_cvt_pk_bf16_f32 v155, v72, v73
	v_cvt_pk_bf16_f32 v156, v66, v67
	v_cvt_pk_bf16_f32 v157, v68, v69
	s_waitcnt lgkmcnt(0)
	global_store_dwordx4 v[246:247], v[248:251], off
	ds_write_b128 v244, v[154:157]
	v_lshl_add_u64 v[246:247], v[140:141], 0, v[252:253]
	ds_read_b128 v[248:251], v245
	v_mad_i64_i32 v[140:141], s[18:19], s20, v152, 0
	v_lshl_add_u64 v[140:141], v[140:141], 1, s[8:9]
	v_lshl_add_u64 v[140:141], v[140:141], 0, v[142:143]
	v_cvt_pk_bf16_f32 v152, v62, v63
	v_cvt_pk_bf16_f32 v153, v64, v65
	v_cvt_pk_bf16_f32 v154, v58, v59
	v_cvt_pk_bf16_f32 v155, v60, v61
	s_waitcnt lgkmcnt(0)
	global_store_dwordx4 v[246:247], v[248:251], off offset:256
	ds_write_b128 v244, v[152:155]
	v_lshl_add_u64 v[246:247], v[140:141], 0, v[252:253]
	ds_read_b128 v[248:251], v245
	s_nop 1
	v_cvt_pk_bf16_f32 v152, v50, v51
	v_cvt_pk_bf16_f32 v153, v52, v53
	v_cvt_pk_bf16_f32 v154, v42, v43
	v_cvt_pk_bf16_f32 v155, v44, v45
	s_waitcnt lgkmcnt(0)
	global_store_dwordx4 v[246:247], v[248:251], off
	ds_write_b128 v244, v[152:155]
	v_lshl_add_u64 v[246:247], v[140:141], 0, v[252:253]
	ds_read_b128 v[248:251], v245
	v_mad_i64_i32 v[140:141], s[18:19], s20, v151, 0
	v_lshl_add_u64 v[140:141], v[140:141], 1, s[8:9]
	v_lshl_add_u64 v[140:141], v[140:141], 0, v[142:143]
	v_cvt_pk_bf16_f32 v152, v54, v55
	v_cvt_pk_bf16_f32 v153, v56, v57
	v_cvt_pk_bf16_f32 v154, v46, v47
	v_cvt_pk_bf16_f32 v155, v48, v49
	s_waitcnt lgkmcnt(0)
	global_store_dwordx4 v[246:247], v[248:251], off offset:256
	ds_write_b128 v244, v[152:155]
	v_lshl_add_u64 v[246:247], v[140:141], 0, v[252:253]
	ds_read_b128 v[248:251], v245
	s_nop 1
	v_cvt_pk_bf16_f32 v152, v34, v35
	v_cvt_pk_bf16_f32 v153, v36, v37
	v_cvt_pk_bf16_f32 v154, v26, v27
	v_cvt_pk_bf16_f32 v155, v28, v29
	s_waitcnt lgkmcnt(0)
	global_store_dwordx4 v[246:247], v[248:251], off
	ds_write_b128 v244, v[152:155]
	v_lshl_add_u64 v[246:247], v[140:141], 0, v[252:253]
	ds_read_b128 v[248:251], v245
	v_mad_i64_i32 v[140:141], s[18:19], s20, v150, 0
	v_lshl_add_u64 v[140:141], v[140:141], 1, s[8:9]
	v_lshl_add_u64 v[140:141], v[140:141], 0, v[142:143]
	v_cvt_pk_bf16_f32 v150, v38, v39
	v_cvt_pk_bf16_f32 v151, v40, v41
	v_cvt_pk_bf16_f32 v152, v30, v31
	v_cvt_pk_bf16_f32 v153, v32, v33
	s_waitcnt lgkmcnt(0)
	global_store_dwordx4 v[246:247], v[248:251], off offset:256
	ds_write_b128 v244, v[150:153]
	v_lshl_add_u64 v[246:247], v[140:141], 0, v[252:253]
	ds_read_b128 v[248:251], v245
	s_nop 1
	v_cvt_pk_bf16_f32 v150, v18, v19
	v_cvt_pk_bf16_f32 v151, v20, v21
	v_cvt_pk_bf16_f32 v152, v10, v11
	v_cvt_pk_bf16_f32 v153, v12, v13
	s_waitcnt lgkmcnt(0)
	global_store_dwordx4 v[246:247], v[248:251], off
	ds_write_b128 v244, v[150:153]
	v_lshl_add_u64 v[246:247], v[140:141], 0, v[252:253]
	ds_read_b128 v[248:251], v245
	v_mad_i64_i32 v[140:141], s[18:19], s20, v149, 0
	v_lshl_add_u64 v[140:141], v[140:141], 1, s[8:9]
	v_lshl_add_u64 v[150:151], v[140:141], 0, v[142:143]
	v_cvt_pk_bf16_f32 v140, v22, v23
	v_cvt_pk_bf16_f32 v141, v24, v25
	v_cvt_pk_bf16_f32 v142, v14, v15
	v_cvt_pk_bf16_f32 v143, v16, v17
	s_waitcnt lgkmcnt(0)
	global_store_dwordx4 v[246:247], v[248:251], off offset:256
	ds_write_b128 v244, v[140:143]
	v_lshl_add_u64 v[246:247], v[150:151], 0, v[252:253]
	ds_read_b128 v[248:251], v245
	s_nop 1
	v_cvt_pk_bf16_f32 v140, v6, v7
	v_cvt_pk_bf16_f32 v141, v8, v9
	v_cvt_pk_bf16_f32 v142, v2, v3
	v_cvt_pk_bf16_f32 v143, v4, v5
	s_waitcnt lgkmcnt(0)
	global_store_dwordx4 v[246:247], v[248:251], off
	ds_write_b128 v244, v[140:143]
	v_lshl_add_u64 v[246:247], v[150:151], 0, v[252:253]
	ds_read_b128 v[248:251], v245
	s_waitcnt lgkmcnt(0)
	global_store_dwordx4 v[246:247], v[248:251], off offset:256

; __device__ __forceinline__ unsigned cvt_pk_bf16(float lo, float hi) { unsigned r; asm volatile("v_cvt_pk_bf16_f32 %0, %1, %2" : "=v"(r) : "v"(lo), "v"(hi)); return r; }
;     __device__ __forceinline__ void operator()(const f32x4 (&acc)[2][2][4][2], const Unit& u, int wr, int wc, int fr, int fq) const {
;     ...
;         if (u.part >= 0) {
;             bf16_t* Pp = P + (size_t)u.part * pstride; const int col0 = u.pn * BM + wc * 32 + 8 * fq;
; #pragma unroll
;             for (int ai = 0; ai < 2; ++ai)
; #pragma unroll
;                 for (int m = 0; m < 4; ++m) { bf16_t* rowp = Pp + (size_t)(row0 + ai * HALF + m * 16 - prow0) * ldc + col0;
; #pragma unroll
;                     for (int bj = 0; bj < 2; ++bj) { const f32x4 v0 = acc[ai][bj][m][0], v1 = acc[ai][bj][m][1];
;                         u32x4 w; w.x = cvt_pk_bf16(v0[0], v0[1]); w.y = cvt_pk_bf16(v0[2], v0[3]); w.z = cvt_pk_bf16(v1[0], v1[1]); w.w = cvt_pk_bf16(v1[2], v1[3]);
;                         *(u32x4*)(rowp + bj * HALF) = w; } }
.LBB0_370:
	s_mov_b32 s31, s89
	s_lshl_b64 s[18:19], s[30:31], 23
	s_add_u32 s18, s70, s18
	v_lshl_or_b32 v140, s67, 8, v146
	s_addc_u32 s19, s71, s19
	v_ashrrev_i32_e32 v141, 31, v140
	v_add_u32_e32 v142, 0xffffc000, v148
	v_lshl_add_u64 v[140:141], v[140:141], 1, s[18:19]
	v_mad_i64_i32 v[142:143], s[18:19], s20, v142, 0
	v_lshl_add_u64 v[142:143], v[142:143], 1, v[140:141]
	v_cvt_pk_bf16_f32 v126, v126, v127
	v_cvt_pk_bf16_f32 v127, v128, v129
	v_cvt_pk_bf16_f32 v128, v122, v123
	v_cvt_pk_bf16_f32 v129, v124, v125
	ds_write_b128 v244, v[126:129]
	v_lshl_add_u64 v[246:247], v[142:143], 0, v[252:253]
	ds_read_b128 v[248:251], v245
	v_cvt_pk_bf16_f32 v114, v114, v115
	v_cvt_pk_bf16_f32 v115, v116, v117
	v_cvt_pk_bf16_f32 v116, v106, v107
	v_add_u32_e32 v106, 0xffffc010, v148
	v_mad_i64_i32 v[106:107], s[18:19], s20, v106, 0
	v_cvt_pk_bf16_f32 v117, v108, v109
	s_waitcnt lgkmcnt(0)
	global_store_dwordx4 v[246:247], v[248:251], off
	ds_write_b128 v244, v[114:117]
	v_lshl_add_u64 v[246:247], v[142:143], 0, v[252:253]
	ds_read_b128 v[248:251], v245
	s_nop 1
	v_lshl_add_u64 v[114:115], v[106:107], 1, v[140:141]
	v_cvt_pk_bf16_f32 v106, v118, v119
	v_cvt_pk_bf16_f32 v107, v120, v121
	v_cvt_pk_bf16_f32 v108, v110, v111
	v_cvt_pk_bf16_f32 v109, v112, v113
	s_waitcnt lgkmcnt(0)
	global_store_dwordx4 v[246:247], v[248:251], off offset:256
	ds_write_b128 v244, v[106:109]
	v_lshl_add_u64 v[246:247], v[114:115], 0, v[252:253]
	ds_read_b128 v[248:251], v245
	v_cvt_pk_bf16_f32 v98, v98, v99
	v_cvt_pk_bf16_f32 v99, v100, v101
	v_cvt_pk_bf16_f32 v100, v90, v91
	v_add_u32_e32 v90, 0xffffc020, v148
	v_mad_i64_i32 v[90:91], s[18:19], s20, v90, 0
	v_cvt_pk_bf16_f32 v101, v92, v93
	s_waitcnt lgkmcnt(0)
	global_store_dwordx4 v[246:247], v[248:251], off
	ds_write_b128 v244, v[98:101]
	v_lshl_add_u64 v[246:247], v[114:115], 0, v[252:253]
	ds_read_b128 v[248:251], v245
	s_nop 1
	v_lshl_add_u64 v[98:99], v[90:91], 1, v[140:141]
	v_cvt_pk_bf16_f32 v90, v102, v103
	v_cvt_pk_bf16_f32 v91, v104, v105
	v_cvt_pk_bf16_f32 v92, v94, v95
	v_cvt_pk_bf16_f32 v93, v96, v97
	s_waitcnt lgkmcnt(0)
	global_store_dwordx4 v[246:247], v[248:251], off offset:256
	ds_write_b128 v244, v[90:93]
	v_lshl_add_u64 v[246:247], v[98:99], 0, v[252:253]
	ds_read_b128 v[248:251], v245
	v_cvt_pk_bf16_f32 v82, v82, v83
	v_cvt_pk_bf16_f32 v83, v84, v85
	v_cvt_pk_bf16_f32 v84, v74, v75
	v_add_u32_e32 v74, 0xffffc030, v148
	v_mad_i64_i32 v[74:75], s[18:19], s20, v74, 0
	v_cvt_pk_bf16_f32 v85, v76, v77
	s_waitcnt lgkmcnt(0)
	global_store_dwordx4 v[246:247], v[248:251], off
	ds_write_b128 v244, v[82:85]
	v_lshl_add_u64 v[246:247], v[98:99], 0, v[252:253]
	ds_read_b128 v[248:251], v245
	s_nop 1
	v_lshl_add_u64 v[82:83], v[74:75], 1, v[140:141]
	v_cvt_pk_bf16_f32 v74, v86, v87
	v_cvt_pk_bf16_f32 v75, v88, v89
	v_cvt_pk_bf16_f32 v76, v78, v79
	v_cvt_pk_bf16_f32 v77, v80, v81
	s_waitcnt lgkmcnt(0)
	global_store_dwordx4 v[246:247], v[248:251], off offset:256
	ds_write_b128 v244, v[74:77]
	v_lshl_add_u64 v[246:247], v[82:83], 0, v[252:253]
	ds_read_b128 v[248:251], v245
	v_cvt_pk_bf16_f32 v70, v70, v71
	v_cvt_pk_bf16_f32 v71, v72, v73
	v_cvt_pk_bf16_f32 v72, v66, v67
	v_add_u32_e32 v66, 0xffffc080, v148
	v_mad_i64_i32 v[66:67], s[18:19], s20, v66, 0
	v_lshl_add_u64 v[66:67], v[66:67], 1, v[140:141]
	v_cvt_pk_bf16_f32 v73, v68, v69
	s_waitcnt lgkmcnt(0)
	global_store_dwordx4 v[246:247], v[248:251], off
	ds_write_b128 v244, v[70:73]
	v_lshl_add_u64 v[246:247], v[82:83], 0, v[252:253]
	ds_read_b128 v[248:251], v245
	v_cvt_pk_bf16_f32 v62, v62, v63
	v_cvt_pk_bf16_f32 v63, v64, v65
	v_cvt_pk_bf16_f32 v64, v58, v59
	v_cvt_pk_bf16_f32 v65, v60, v61
	s_waitcnt lgkmcnt(0)
	global_store_dwordx4 v[246:247], v[248:251], off offset:256
	ds_write_b128 v244, v[62:65]
	v_lshl_add_u64 v[246:247], v[66:67], 0, v[252:253]
	ds_read_b128 v[248:251], v245
	v_cvt_pk_bf16_f32 v50, v50, v51
	v_cvt_pk_bf16_f32 v51, v52, v53
	v_cvt_pk_bf16_f32 v52, v42, v43
	v_add_u32_e32 v42, 0xffffc090, v148
	v_mad_i64_i32 v[42:43], s[18:19], s20, v42, 0
	v_cvt_pk_bf16_f32 v53, v44, v45
	s_waitcnt lgkmcnt(0)
	global_store_dwordx4 v[246:247], v[248:251], off
	ds_write_b128 v244, v[50:53]
	v_lshl_add_u64 v[246:247], v[66:67], 0, v[252:253]
	ds_read_b128 v[248:251], v245
	s_nop 1
	v_lshl_add_u64 v[50:51], v[42:43], 1, v[140:141]
	v_cvt_pk_bf16_f32 v42, v54, v55
	v_cvt_pk_bf16_f32 v43, v56, v57
	v_cvt_pk_bf16_f32 v44, v46, v47
	v_cvt_pk_bf16_f32 v45, v48, v49
	s_waitcnt lgkmcnt(0)
	global_store_dwordx4 v[246:247], v[248:251], off offset:256
	ds_write_b128 v244, v[42:45]
	v_lshl_add_u64 v[246:247], v[50:51], 0, v[252:253]
	ds_read_b128 v[248:251], v245
	v_cvt_pk_bf16_f32 v34, v34, v35
	v_cvt_pk_bf16_f32 v35, v36, v37
	v_cvt_pk_bf16_f32 v36, v26, v27
	v_add_u32_e32 v26, 0xffffc0a0, v148
	v_mad_i64_i32 v[26:27], s[18:19], s20, v26, 0
	v_cvt_pk_bf16_f32 v37, v28, v29
	s_waitcnt lgkmcnt(0)
	global_store_dwordx4 v[246:247], v[248:251], off
	ds_write_b128 v244, v[34:37]
	v_lshl_add_u64 v[246:247], v[50:51], 0, v[252:253]
	ds_read_b128 v[248:251], v245
	s_nop 1
	v_lshl_add_u64 v[34:35], v[26:27], 1, v[140:141]
	v_cvt_pk_bf16_f32 v26, v38, v39
	v_cvt_pk_bf16_f32 v27, v40, v41
	v_cvt_pk_bf16_f32 v28, v30, v31
	v_cvt_pk_bf16_f32 v29, v32, v33
	s_waitcnt lgkmcnt(0)
	global_store_dwordx4 v[246:247], v[248:251], off offset:256
	ds_write_b128 v244, v[26:29]
	v_lshl_add_u64 v[246:247], v[34:35], 0, v[252:253]
	ds_read_b128 v[248:251], v245
	v_cvt_pk_bf16_f32 v18, v18, v19
	v_cvt_pk_bf16_f32 v19, v20, v21
	v_cvt_pk_bf16_f32 v20, v10, v11
	v_add_u32_e32 v10, 0xffffc0b0, v148
	v_mad_i64_i32 v[10:11], s[18:19], s20, v10, 0
	v_cvt_pk_bf16_f32 v21, v12, v13
	s_waitcnt lgkmcnt(0)
	global_store_dwordx4 v[246:247], v[248:251], off
	ds_write_b128 v244, v[18:21]
	v_lshl_add_u64 v[246:247], v[34:35], 0, v[252:253]
	ds_read_b128 v[248:251], v245
	s_nop 1
	v_lshl_add_u64 v[18:19], v[10:11], 1, v[140:141]
	v_cvt_pk_bf16_f32 v10, v22, v23
	v_cvt_pk_bf16_f32 v11, v24, v25
	v_cvt_pk_bf16_f32 v12, v14, v15
	v_cvt_pk_bf16_f32 v13, v16, v17
	s_waitcnt lgkmcnt(0)
	global_store_dwordx4 v[246:247], v[248:251], off offset:256
	ds_write_b128 v244, v[10:13]
	v_lshl_add_u64 v[246:247], v[18:19], 0, v[252:253]
	ds_read_b128 v[248:251], v245
	v_cvt_pk_bf16_f32 v6, v6, v7
	v_cvt_pk_bf16_f32 v7, v8, v9
	v_cvt_pk_bf16_f32 v8, v2, v3
	v_cvt_pk_bf16_f32 v9, v4, v5
	s_waitcnt lgkmcnt(0)
	global_store_dwordx4 v[246:247], v[248:251], off
	ds_write_b128 v244, v[6:9]
	v_lshl_add_u64 v[246:247], v[18:19], 0, v[252:253]
	ds_read_b128 v[248:251], v245
	s_and_b64 vcc, exec, s[40:41]
	s_mov_b64 s[30:31], -1
	s_waitcnt lgkmcnt(0)
	global_store_dwordx4 v[246:247], v[248:251], off offset:256
	s_cbranch_vccnz .LBB0_345
